# byte-phase pin for the attention region: FoX / NSA / SWA tile loops moved from 4 mod 8 to 0 mod 8 with two never-executed pads (GEMM loops keep their phase)
# baseline (speedup 1.0000x reference)
; __device__ __forceinline__ int otid() { int t = threadIdx.x; asm volatile("" : "+v"(t)); return t; }
; #define PG8_LAS __attribute__((address_space(3)))
; __device__ __forceinline__ void attn_phase(lptr L, const Params& P, int layer) {
;     const int tid = otid(), G = gridDim.x;
;     const int blk = (G % 8 == 0) ? (int)(blockIdx.x % 8) * (G / 8) + (int)(blockIdx.x / 8) : (int)blockIdx.x;
;     for (int i = tid; i < 16 * TABP; i += NT) {
;         const int h = i / TABP, d = i - h * TABP - TAB0;
;         float v = 0.f;
;         if (d >= 0) {
;             int bk = d;
;             if (d >= 16) { bk = (d >= 128) ? 31 : 16 + (int)(logf((float)d * (1.f / 16.f)) / logf(8.f) * 16.f); bk = bk > 31 ? 31 : bk; }
;             v = P.in[1][bk * 16 + h] * LOG2E;
;         }
;         lds_st<float>(L + A_TAB + i * 4, v);
;     }
;     __syncthreads();
; __global__ void __launch_bounds__(NT, 2) mk_fwd(Params P) {
;     ...
;             } else if (st == 4) {
;                 pg8::Gemm g{XN, (const bf16_t*)(ws + W_Z), M, 3840, DM}; pg8::StaticOrder S; S.init(M, 3840, G, bx);
;                 EpiZ E{BIG};
;                 pg8::gemm_phase<EpiZ, pg8::StaticOrder, true, true>((PG8_LAS unsigned char*)L, g, S, E);
;     ...
;                 pg8::gemm_phase<EpiZ, pg8::StaticOrder, true, true>((PG8_LAS unsigned char*)L, g, S, E);
;     ...
;             } else if (st == 5) {
;                 compress_phase(L, P, l);
;     ...
;                 __syncthreads(); compress_phase(L, P, l);
;     ...
;             } else if (st == 6) {
;                 attn_phase(L, P, l);
.LBB0_137:
	v_writelane_b32 v255, s76, 55
	s_and_b64 vcc, exec, s[0:1]
	v_writelane_b32 v255, s84, 56
	s_cbranch_vccz .LBB0_745
	s_cmp_gt_i32 s76, 2
	s_mov_b64 s[2:3], -1
	s_cbranch_scc0 .LBB0_745
	s_cmp_gt_i32 s76, 4
	s_mov_b64 s[0:1], -1
	s_cbranch_scc0 .LBB0_691
	s_cmp_gt_i32 s76, 5
	s_cbranch_scc0 .LBB0_153
	v_readlane_b32 s2, v253, 8
	v_readlane_b32 s3, v253, 9
	v_lshlrev_b32_e32 v2, 2, v193
	s_nop 4
	global_load_dword v3, v2, s[2:3]
	s_waitcnt vmcnt(0)
	ds_write_b32 v2, v3
	s_waitcnt lgkmcnt(0)
	s_barrier
	v_mov_b32_e32 v0, v193
	s_movk_i32 s0, 0x1880
	s_nop 0
	v_cmp_gt_i32_e32 vcc, s0, v0
	s_and_saveexec_b64 s[0:1], vcc
	s_cbranch_execz .LBB0_150
	v_lshl_add_u32 v2, v0, 2, v219
	s_mov_b64 s[2:3], 0
	s_branch .LBB0_146
	s_nop 0

; __device__ __forceinline__ void compress_phase(lptr L, const Params& P, int l) {
;     ...
;         __syncthreads();
;         float base = 0.f;
;         for (int w = 0; w < wave; ++w) base += lds_ld<float>(L + w * 4);
;         const float excl = base + inc - tot;
.LBB0_688:
	v_mov_b32_e32 v24, s1
	ds_read_b32 v24, v24
	v_add_u32_e32 v23, -1, v23
	s_add_i32 s1, s1, 4
	v_cmp_eq_u32_e32 vcc, 0, v23
	s_or_b64 s[6:7], vcc, s[6:7]
	s_waitcnt lgkmcnt(0)
	v_add_f32_e32 v22, v22, v24
	s_andn2_b64 exec, exec, s[6:7]
	s_cbranch_execnz .LBB0_688
	s_or_b64 exec, exec, s[6:7]
	s_branch .LBB0_651
	s_nop 0
